# v28 plus both GEMM K-loops: first trip peeled with C=0, accumulator zeroing removed
# baseline (speedup 1.0000x reference)
.LBB0_287:
	s_ashr_i32 s11, s10, 31
	s_lshl_b64 s[12:13], s[10:11], 21
	v_readlane_b32 s14, v253, 43
	v_readlane_b32 s15, v253, 44
	s_add_u32 s12, s14, s12
	s_addc_u32 s13, s15, s13
	s_and_b64 s[14:15], s[0:1], exec
	s_cselect_b32 s11, s13, s17
	s_cselect_b32 s40, s12, s16
	s_ashr_i32 s9, s8, 31
	s_lshl_b64 s[14:15], s[8:9], 21
	s_add_u32 s14, s22, s14
	s_addc_u32 s15, s23, s15
	s_and_b64 s[20:21], s[0:1], exec
	s_cselect_b32 s9, s15, s19
	s_cselect_b32 s41, s14, s18
	s_add_u32 s16, s16, 0x100080
	s_addc_u32 s17, s17, 0
	s_add_u32 s42, s18, 0x100
	s_addc_u32 s43, s19, 0
	s_mov_b32 s46, -2
	s_mov_b64 vcc, 0x80
	s_add_u32 s18, s16, 0xfff00080
	s_addc_u32 s19, s17, -1
	s_add_i32 s47, 0, 0x10000
	s_cmp_eq_u32 s46, 60
	s_cselect_b32 s21, s11, s19
	s_cselect_b32 s20, s40, s18
	v_add_u32_e32 v140, s47, v143
	s_cselect_b32 s19, s9, s43
	s_cselect_b32 s18, s41, s42
	s_add_i32 s48, 0, 0x14000
	ds_read_b128 v[146:149], v140
	ds_read_b128 v[150:153], v140 offset:1024
	ds_read_b128 v[154:157], v140 offset:2048
	ds_read_b128 v[162:165], v140 offset:3072
	v_add_u32_e32 v140, s48, v143
	ds_read_b128 v[166:169], v140
	ds_read_b128 v[170:173], v140 offset:1024
	ds_read_b128 v[174:177], v140 offset:2048
	ds_read_b128 v[178:181], v140 offset:3072
	v_lshl_add_u64 v[140:141], s[16:17], 0, v[136:137]
	s_add_i32 m0, s25, 0xc000
	ds_read_b128 v[182:185], v145
	ds_read_b128 v[186:189], v145 offset:1024
	ds_read_b128 v[190:193], v145 offset:2048
	ds_read_b128 v[194:197], v145 offset:3072
	ds_read_b128 v[198:201], v145 offset:4096
	ds_read_b128 v[202:205], v145 offset:5120
	ds_read_b128 v[218:221], v145 offset:6144
	ds_read_b128 v[222:225], v145 offset:7168
	global_load_lds_dwordx4 v[140:141], off
	v_lshl_add_u64 v[140:141], s[16:17], 0, v[138:139]
	s_add_i32 m0, s25, 0xe000
	s_nop 0
	global_load_lds_dwordx4 v[140:141], off
	s_waitcnt vmcnt(8)
	s_waitcnt lgkmcnt(0)
	s_barrier
	s_setprio 1
	s_waitcnt lgkmcnt(0)
	v_mfma_f32_16x16x32_bf16 v[124:127], v[146:149], v[182:185], 0
	v_mfma_f32_16x16x32_bf16 v[120:123], v[154:157], v[182:185], 0
	v_mfma_f32_16x16x32_bf16 v[116:119], v[146:149], v[190:193], 0
	v_mfma_f32_16x16x32_bf16 v[112:115], v[154:157], v[190:193], 0
	v_mfma_f32_16x16x32_bf16 v[100:103], v[146:149], v[198:201], 0
	v_mfma_f32_16x16x32_bf16 v[96:99], v[154:157], v[198:201], 0
	v_mfma_f32_16x16x32_bf16 v[84:87], v[146:149], v[218:221], 0
	v_mfma_f32_16x16x32_bf16 v[80:83], v[154:157], v[218:221], 0
	v_mfma_f32_16x16x32_bf16 v[124:127], v[150:153], v[186:189], v[124:127]
	v_mfma_f32_16x16x32_bf16 v[120:123], v[162:165], v[186:189], v[120:123]
	v_mfma_f32_16x16x32_bf16 v[116:119], v[150:153], v[194:197], v[116:119]
	v_mfma_f32_16x16x32_bf16 v[112:115], v[162:165], v[194:197], v[112:115]
	v_mfma_f32_16x16x32_bf16 v[100:103], v[150:153], v[202:205], v[100:103]
	v_mfma_f32_16x16x32_bf16 v[96:99], v[162:165], v[202:205], v[96:99]
	v_mfma_f32_16x16x32_bf16 v[84:87], v[150:153], v[222:225], v[84:87]
	v_mfma_f32_16x16x32_bf16 v[80:83], v[162:165], v[222:225], v[80:83]
	s_setprio 0
	s_setprio 1
	v_mfma_f32_16x16x32_bf16 v[108:111], v[166:169], v[182:185], 0
	v_mfma_f32_16x16x32_bf16 v[104:107], v[174:177], v[182:185], 0
	v_mfma_f32_16x16x32_bf16 v[92:95], v[166:169], v[190:193], 0
	v_mfma_f32_16x16x32_bf16 v[88:91], v[174:177], v[190:193], 0
	v_mfma_f32_16x16x32_bf16 v[76:79], v[166:169], v[198:201], 0
	v_mfma_f32_16x16x32_bf16 v[72:75], v[174:177], v[198:201], 0
	v_mfma_f32_16x16x32_bf16 v[68:71], v[166:169], v[218:221], 0
	v_mfma_f32_16x16x32_bf16 v[64:67], v[174:177], v[218:221], 0
	v_mfma_f32_16x16x32_bf16 v[108:111], v[170:173], v[186:189], v[108:111]
	v_mfma_f32_16x16x32_bf16 v[104:107], v[178:181], v[186:189], v[104:107]
	v_mfma_f32_16x16x32_bf16 v[92:95], v[170:173], v[194:197], v[92:95]
	v_mfma_f32_16x16x32_bf16 v[88:91], v[178:181], v[194:197], v[88:91]
	v_mfma_f32_16x16x32_bf16 v[76:79], v[170:173], v[202:205], v[76:79]
	v_mfma_f32_16x16x32_bf16 v[72:75], v[178:181], v[202:205], v[72:75]
	v_mfma_f32_16x16x32_bf16 v[68:71], v[170:173], v[222:225], v[68:71]
	v_mfma_f32_16x16x32_bf16 v[64:67], v[178:181], v[222:225], v[64:67]
	s_setprio 0
	s_barrier
	s_add_i32 s47, s47, s24
	v_lshl_add_u64 v[140:141], s[18:19], 0, v[160:161]
	s_mov_b32 m0, s47
	ds_read_b128 v[182:185], v145 offset:16384
	ds_read_b128 v[186:189], v145 offset:17408
	ds_read_b128 v[190:193], v145 offset:18432
	ds_read_b128 v[194:197], v145 offset:19456
	ds_read_b128 v[198:201], v145 offset:20480
	ds_read_b128 v[202:205], v145 offset:21504
	ds_read_b128 v[218:221], v145 offset:22528
	ds_read_b128 v[222:225], v145 offset:23552
	global_load_lds_dwordx4 v[140:141], off
	s_add_i32 m0, s47, 0x2000
	s_add_u32 s50, s18, 0x100000
	v_lshl_add_u64 v[158:159], s[18:19], 0, v[128:129]
	s_addc_u32 s51, s19, 0
	s_add_i32 s47, s48, s24
	global_load_lds_dwordx4 v[158:159], off
	v_lshl_add_u64 v[212:213], s[50:51], 0, v[160:161]
	s_mov_b32 m0, s47
	v_lshl_add_u64 v[226:227], s[20:21], 0, v[130:131]
	global_load_lds_dwordx4 v[212:213], off
	v_lshl_add_u64 v[212:213], s[50:51], 0, v[128:129]
	s_add_i32 m0, s47, 0x2000
	s_nop 0
	global_load_lds_dwordx4 v[212:213], off
	v_lshl_add_u64 v[212:213], s[20:21], 0, v[132:133]
	s_mov_b32 m0, s25
	s_nop 0
	global_load_lds_dwordx4 v[212:213], off
	s_mov_b32 m0, s26
	s_nop 0
	global_load_lds_dwordx4 v[226:227], off
	s_waitcnt vmcnt(8)
	s_waitcnt lgkmcnt(0)
	s_barrier
	s_setprio 1
	s_waitcnt lgkmcnt(0)
	v_mfma_f32_16x16x32_bf16 v[60:63], v[146:149], v[182:185], 0
	v_mfma_f32_16x16x32_bf16 v[56:59], v[154:157], v[182:185], 0
	v_mfma_f32_16x16x32_bf16 v[52:55], v[146:149], v[190:193], 0
	v_mfma_f32_16x16x32_bf16 v[48:51], v[154:157], v[190:193], 0
	v_mfma_f32_16x16x32_bf16 v[36:39], v[146:149], v[198:201], 0
	v_mfma_f32_16x16x32_bf16 v[32:35], v[154:157], v[198:201], 0
	v_mfma_f32_16x16x32_bf16 v[20:23], v[146:149], v[218:221], 0
	v_mfma_f32_16x16x32_bf16 v[16:19], v[154:157], v[218:221], 0
	v_mfma_f32_16x16x32_bf16 v[60:63], v[150:153], v[186:189], v[60:63]
	v_mfma_f32_16x16x32_bf16 v[56:59], v[162:165], v[186:189], v[56:59]
	v_mfma_f32_16x16x32_bf16 v[52:55], v[150:153], v[194:197], v[52:55]
	v_mfma_f32_16x16x32_bf16 v[48:51], v[162:165], v[194:197], v[48:51]
	v_mfma_f32_16x16x32_bf16 v[36:39], v[150:153], v[202:205], v[36:39]
	v_mfma_f32_16x16x32_bf16 v[32:35], v[162:165], v[202:205], v[32:35]
	v_mfma_f32_16x16x32_bf16 v[20:23], v[150:153], v[222:225], v[20:23]
	v_mfma_f32_16x16x32_bf16 v[16:19], v[162:165], v[222:225], v[16:19]
	s_setprio 0
	s_setprio 1
	v_mfma_f32_16x16x32_bf16 v[44:47], v[166:169], v[182:185], 0
	v_mfma_f32_16x16x32_bf16 v[40:43], v[174:177], v[182:185], 0
	v_mfma_f32_16x16x32_bf16 v[28:31], v[166:169], v[190:193], 0
	v_mfma_f32_16x16x32_bf16 v[24:27], v[174:177], v[190:193], 0
	v_mfma_f32_16x16x32_bf16 v[12:15], v[166:169], v[198:201], 0
	v_mfma_f32_16x16x32_bf16 v[8:11], v[174:177], v[198:201], 0
	v_mfma_f32_16x16x32_bf16 v[4:7], v[166:169], v[218:221], 0
	v_mfma_f32_16x16x32_bf16 v[0:3], v[174:177], v[218:221], 0
	v_mfma_f32_16x16x32_bf16 v[44:47], v[170:173], v[186:189], v[44:47]
	v_mfma_f32_16x16x32_bf16 v[40:43], v[178:181], v[186:189], v[40:43]
	v_mfma_f32_16x16x32_bf16 v[28:31], v[170:173], v[194:197], v[28:31]
	v_mfma_f32_16x16x32_bf16 v[24:27], v[178:181], v[194:197], v[24:27]
	v_mfma_f32_16x16x32_bf16 v[12:15], v[170:173], v[202:205], v[12:15]
	v_mfma_f32_16x16x32_bf16 v[8:11], v[178:181], v[202:205], v[8:11]
	v_mfma_f32_16x16x32_bf16 v[4:7], v[170:173], v[222:225], v[4:7]
	v_mfma_f32_16x16x32_bf16 v[0:3], v[178:181], v[222:225], v[0:3]
	s_setprio 0
	s_barrier
	s_add_i32 s47, 0, 0x18000
	s_add_i32 s48, 0, 0x1c000
	v_add_u32_e32 v162, s47, v143
	v_add_u32_e32 v178, s48, v143
	ds_read_b128 v[146:149], v162
	ds_read_b128 v[150:153], v162 offset:1024
	ds_read_b128 v[154:157], v162 offset:2048
	ds_read_b128 v[162:165], v162 offset:3072
	ds_read_b128 v[166:169], v178
	ds_read_b128 v[170:173], v178 offset:1024
	ds_read_b128 v[174:177], v178 offset:2048
	ds_read_b128 v[178:181], v178 offset:3072
	s_add_u32 s20, s20, 0x100000
	s_addc_u32 s21, s21, 0
	s_mov_b32 m0, s27
	v_lshl_add_u64 v[228:229], s[20:21], 0, v[132:133]
	ds_read_b128 v[182:185], v145 offset:32768
	ds_read_b128 v[186:189], v145 offset:33792
	ds_read_b128 v[190:193], v145 offset:34816
	ds_read_b128 v[194:197], v145 offset:35840
	ds_read_b128 v[198:201], v145 offset:36864
	ds_read_b128 v[202:205], v145 offset:37888
	ds_read_b128 v[218:221], v145 offset:38912
	ds_read_b128 v[222:225], v145 offset:39936
	global_load_lds_dwordx4 v[228:229], off
	v_lshl_add_u64 v[228:229], s[20:21], 0, v[130:131]
	s_mov_b32 m0, s28
	s_nop 0
	global_load_lds_dwordx4 v[228:229], off
	s_waitcnt vmcnt(8)
	s_waitcnt lgkmcnt(0)
	s_barrier
	s_setprio 1
	s_waitcnt lgkmcnt(0)
	v_mfma_f32_16x16x32_bf16 v[124:127], v[146:149], v[182:185], v[124:127]
	v_mfma_f32_16x16x32_bf16 v[120:123], v[154:157], v[182:185], v[120:123]
	v_mfma_f32_16x16x32_bf16 v[116:119], v[146:149], v[190:193], v[116:119]
	v_mfma_f32_16x16x32_bf16 v[112:115], v[154:157], v[190:193], v[112:115]
	v_mfma_f32_16x16x32_bf16 v[100:103], v[146:149], v[198:201], v[100:103]
	v_mfma_f32_16x16x32_bf16 v[96:99], v[154:157], v[198:201], v[96:99]
	v_mfma_f32_16x16x32_bf16 v[84:87], v[146:149], v[218:221], v[84:87]
	v_mfma_f32_16x16x32_bf16 v[80:83], v[154:157], v[218:221], v[80:83]
	v_mfma_f32_16x16x32_bf16 v[124:127], v[150:153], v[186:189], v[124:127]
	v_mfma_f32_16x16x32_bf16 v[120:123], v[162:165], v[186:189], v[120:123]
	v_mfma_f32_16x16x32_bf16 v[116:119], v[150:153], v[194:197], v[116:119]
	v_mfma_f32_16x16x32_bf16 v[112:115], v[162:165], v[194:197], v[112:115]
	v_mfma_f32_16x16x32_bf16 v[100:103], v[150:153], v[202:205], v[100:103]
	v_mfma_f32_16x16x32_bf16 v[96:99], v[162:165], v[202:205], v[96:99]
	v_mfma_f32_16x16x32_bf16 v[84:87], v[150:153], v[222:225], v[84:87]
	v_mfma_f32_16x16x32_bf16 v[80:83], v[162:165], v[222:225], v[80:83]
	s_setprio 0
	s_setprio 1
	v_mfma_f32_16x16x32_bf16 v[108:111], v[166:169], v[182:185], v[108:111]
	v_mfma_f32_16x16x32_bf16 v[104:107], v[174:177], v[182:185], v[104:107]
	v_mfma_f32_16x16x32_bf16 v[92:95], v[166:169], v[190:193], v[92:95]
	v_mfma_f32_16x16x32_bf16 v[88:91], v[174:177], v[190:193], v[88:91]
	v_mfma_f32_16x16x32_bf16 v[76:79], v[166:169], v[198:201], v[76:79]
	v_mfma_f32_16x16x32_bf16 v[72:75], v[174:177], v[198:201], v[72:75]
	v_mfma_f32_16x16x32_bf16 v[68:71], v[166:169], v[218:221], v[68:71]
	v_mfma_f32_16x16x32_bf16 v[64:67], v[174:177], v[218:221], v[64:67]
	v_mfma_f32_16x16x32_bf16 v[108:111], v[170:173], v[186:189], v[108:111]
	v_mfma_f32_16x16x32_bf16 v[104:107], v[178:181], v[186:189], v[104:107]
	v_mfma_f32_16x16x32_bf16 v[92:95], v[170:173], v[194:197], v[92:95]
	v_mfma_f32_16x16x32_bf16 v[88:91], v[178:181], v[194:197], v[88:91]
	v_mfma_f32_16x16x32_bf16 v[76:79], v[170:173], v[202:205], v[76:79]
	v_mfma_f32_16x16x32_bf16 v[72:75], v[178:181], v[202:205], v[72:75]
	v_mfma_f32_16x16x32_bf16 v[68:71], v[170:173], v[222:225], v[68:71]
	v_mfma_f32_16x16x32_bf16 v[64:67], v[178:181], v[222:225], v[64:67]
	s_setprio 0
	s_barrier
	s_add_i32 s20, s47, s24
	v_lshl_add_u64 v[140:141], v[140:141], 0, vcc
	s_mov_b32 m0, s20
	ds_read_b128 v[182:185], v145 offset:49152
	ds_read_b128 v[186:189], v145 offset:50176
	ds_read_b128 v[190:193], v145 offset:51200
	ds_read_b128 v[194:197], v145 offset:52224
	ds_read_b128 v[198:201], v145 offset:53248
	ds_read_b128 v[202:205], v145 offset:54272
	ds_read_b128 v[218:221], v145 offset:55296
	ds_read_b128 v[222:225], v145 offset:56320
	global_load_lds_dwordx4 v[140:141], off
	s_add_i32 m0, s20, 0x2000
	s_add_u32 s18, s18, 0x100080
	v_lshl_add_u64 v[140:141], v[158:159], 0, vcc
	s_addc_u32 s19, s19, 0
	s_add_i32 s20, s48, s24
	global_load_lds_dwordx4 v[140:141], off
	v_lshl_add_u64 v[140:141], s[18:19], 0, v[160:161]
	s_mov_b32 m0, s20
	s_nop 0
	global_load_lds_dwordx4 v[140:141], off
	v_lshl_add_u64 v[140:141], s[18:19], 0, v[128:129]
	s_add_i32 m0, s20, 0x2000
	s_nop 0
	global_load_lds_dwordx4 v[140:141], off
	v_lshl_add_u64 v[140:141], v[212:213], 0, vcc
	s_mov_b32 m0, s30
	s_nop 0
	global_load_lds_dwordx4 v[140:141], off
	v_lshl_add_u64 v[140:141], v[226:227], 0, vcc
	s_mov_b32 m0, s31
	s_nop 0
	global_load_lds_dwordx4 v[140:141], off
	s_waitcnt vmcnt(8)
	s_waitcnt lgkmcnt(0)
	s_barrier
	s_setprio 1
	s_waitcnt lgkmcnt(0)
	v_mfma_f32_16x16x32_bf16 v[60:63], v[146:149], v[182:185], v[60:63]
	v_mfma_f32_16x16x32_bf16 v[56:59], v[154:157], v[182:185], v[56:59]
	v_mfma_f32_16x16x32_bf16 v[52:55], v[146:149], v[190:193], v[52:55]
	v_mfma_f32_16x16x32_bf16 v[48:51], v[154:157], v[190:193], v[48:51]
	v_mfma_f32_16x16x32_bf16 v[36:39], v[146:149], v[198:201], v[36:39]
	v_mfma_f32_16x16x32_bf16 v[32:35], v[154:157], v[198:201], v[32:35]
	v_mfma_f32_16x16x32_bf16 v[20:23], v[146:149], v[218:221], v[20:23]
	v_mfma_f32_16x16x32_bf16 v[16:19], v[154:157], v[218:221], v[16:19]
	v_mfma_f32_16x16x32_bf16 v[60:63], v[150:153], v[186:189], v[60:63]
	v_mfma_f32_16x16x32_bf16 v[56:59], v[162:165], v[186:189], v[56:59]
	v_mfma_f32_16x16x32_bf16 v[52:55], v[150:153], v[194:197], v[52:55]
	v_mfma_f32_16x16x32_bf16 v[48:51], v[162:165], v[194:197], v[48:51]
	v_mfma_f32_16x16x32_bf16 v[36:39], v[150:153], v[202:205], v[36:39]
	v_mfma_f32_16x16x32_bf16 v[32:35], v[162:165], v[202:205], v[32:35]
	v_mfma_f32_16x16x32_bf16 v[20:23], v[150:153], v[222:225], v[20:23]
	v_mfma_f32_16x16x32_bf16 v[16:19], v[162:165], v[222:225], v[16:19]
	s_setprio 0
	s_setprio 1
	v_mfma_f32_16x16x32_bf16 v[44:47], v[166:169], v[182:185], v[44:47]
	v_mfma_f32_16x16x32_bf16 v[40:43], v[174:177], v[182:185], v[40:43]
	v_mfma_f32_16x16x32_bf16 v[28:31], v[166:169], v[190:193], v[28:31]
	v_mfma_f32_16x16x32_bf16 v[24:27], v[174:177], v[190:193], v[24:27]
	v_mfma_f32_16x16x32_bf16 v[12:15], v[166:169], v[198:201], v[12:15]
	v_mfma_f32_16x16x32_bf16 v[8:11], v[174:177], v[198:201], v[8:11]
	v_mfma_f32_16x16x32_bf16 v[4:7], v[166:169], v[218:221], v[4:7]
	v_mfma_f32_16x16x32_bf16 v[0:3], v[174:177], v[218:221], v[0:3]
	v_mfma_f32_16x16x32_bf16 v[44:47], v[170:173], v[186:189], v[44:47]
	v_mfma_f32_16x16x32_bf16 v[40:43], v[178:181], v[186:189], v[40:43]
	v_mfma_f32_16x16x32_bf16 v[28:31], v[170:173], v[194:197], v[28:31]
	v_mfma_f32_16x16x32_bf16 v[24:27], v[178:181], v[194:197], v[24:27]
	v_mfma_f32_16x16x32_bf16 v[12:15], v[170:173], v[202:205], v[12:15]
	v_mfma_f32_16x16x32_bf16 v[8:11], v[178:181], v[202:205], v[8:11]
	v_mfma_f32_16x16x32_bf16 v[4:7], v[170:173], v[222:225], v[4:7]
	v_mfma_f32_16x16x32_bf16 v[0:3], v[178:181], v[222:225], v[0:3]
	s_setprio 0
	s_barrier
	s_add_i32 s46, s46, 2
	s_add_u32 s16, s16, 0x100
	s_addc_u32 s17, s17, 0
	s_add_u32 s42, s42, 0x100
	s_addc_u32 s43, s43, 0
	s_cmp_gt_u32 s46, 61

.LBB0_929:
	s_ashr_i32 s9, s8, 31
	s_lshl_b64 s[10:11], s[8:9], 21
	v_readlane_b32 s12, v253, 43
	v_readlane_b32 s13, v253, 44
	s_add_u32 s10, s12, s10
	s_addc_u32 s11, s13, s11
	s_and_b64 s[12:13], s[0:1], exec
	s_cselect_b32 s9, s11, s15
	s_cselect_b32 s36, s10, s14
	s_ashr_i32 s7, s6, 31
	s_lshl_b64 s[12:13], s[6:7], 21
	s_add_u32 s12, s20, s12
	s_addc_u32 s13, s21, s13
	s_and_b64 s[18:19], s[0:1], exec
	s_cselect_b32 s7, s13, s17
	s_cselect_b32 s37, s12, s16
	s_add_u32 s14, s14, 0x100080
	s_addc_u32 s15, s15, 0
	s_add_u32 s40, s16, 0x100
	s_addc_u32 s41, s17, 0
	s_mov_b32 s42, -2
	s_mov_b64 vcc, 0x80
	s_add_u32 s16, s14, 0xfff00080
	s_addc_u32 s17, s15, -1
	s_add_i32 s43, 0, 0x10000
	s_cmp_eq_u32 s42, 60
	s_cselect_b32 s19, s9, s17
	s_cselect_b32 s18, s36, s16
	s_cselect_b32 s17, s7, s41
	s_cselect_b32 s16, s37, s40
	s_add_i32 s48, 0, 0x14000
	v_add_u32_e32 v154, s43, v139
	v_add_u32_e32 v158, s48, v139
	ds_read_b128 v[142:145], v154
	ds_read_b128 v[146:149], v154 offset:1024
	ds_read_b128 v[150:153], v154 offset:2048
	ds_read_b128 v[154:157], v154 offset:3072
	ds_read_b128 v[162:165], v158
	ds_read_b128 v[166:169], v158 offset:1024
	ds_read_b128 v[170:173], v158 offset:2048
	ds_read_b128 v[174:177], v158 offset:3072
	v_lshl_add_u64 v[158:159], s[14:15], 0, v[134:135]
	s_add_i32 m0, s23, 0xc000
	ds_read_b128 v[178:181], v141
	ds_read_b128 v[182:185], v141 offset:1024
	ds_read_b128 v[186:189], v141 offset:2048
	ds_read_b128 v[190:193], v141 offset:3072
	ds_read_b128 v[194:197], v141 offset:4096
	ds_read_b128 v[198:201], v141 offset:5120
	ds_read_b128 v[202:205], v141 offset:6144
	ds_read_b128 v[218:221], v141 offset:7168
	global_load_lds_dwordx4 v[158:159], off
	v_lshl_add_u64 v[158:159], s[14:15], 0, v[136:137]
	s_add_i32 m0, s23, 0xe000
	s_nop 0
	global_load_lds_dwordx4 v[158:159], off
	s_waitcnt vmcnt(8)
	s_waitcnt lgkmcnt(0)
	s_barrier
	s_setprio 1
	s_waitcnt lgkmcnt(0)
	v_mfma_f32_16x16x32_bf16 v[124:127], v[142:145], v[178:181], 0
	v_mfma_f32_16x16x32_bf16 v[120:123], v[150:153], v[178:181], 0
	v_mfma_f32_16x16x32_bf16 v[116:119], v[142:145], v[186:189], 0
	v_mfma_f32_16x16x32_bf16 v[112:115], v[150:153], v[186:189], 0
	v_mfma_f32_16x16x32_bf16 v[100:103], v[142:145], v[194:197], 0
	v_mfma_f32_16x16x32_bf16 v[96:99], v[150:153], v[194:197], 0
	v_mfma_f32_16x16x32_bf16 v[84:87], v[142:145], v[202:205], 0
	v_mfma_f32_16x16x32_bf16 v[80:83], v[150:153], v[202:205], 0
	v_mfma_f32_16x16x32_bf16 v[124:127], v[146:149], v[182:185], v[124:127]
	v_mfma_f32_16x16x32_bf16 v[120:123], v[154:157], v[182:185], v[120:123]
	v_mfma_f32_16x16x32_bf16 v[116:119], v[146:149], v[190:193], v[116:119]
	v_mfma_f32_16x16x32_bf16 v[112:115], v[154:157], v[190:193], v[112:115]
	v_mfma_f32_16x16x32_bf16 v[100:103], v[146:149], v[198:201], v[100:103]
	v_mfma_f32_16x16x32_bf16 v[96:99], v[154:157], v[198:201], v[96:99]
	v_mfma_f32_16x16x32_bf16 v[84:87], v[146:149], v[218:221], v[84:87]
	v_mfma_f32_16x16x32_bf16 v[80:83], v[154:157], v[218:221], v[80:83]
	s_setprio 0
	s_setprio 1
	v_mfma_f32_16x16x32_bf16 v[108:111], v[162:165], v[178:181], 0
	v_mfma_f32_16x16x32_bf16 v[104:107], v[170:173], v[178:181], 0
	v_mfma_f32_16x16x32_bf16 v[92:95], v[162:165], v[186:189], 0
	v_mfma_f32_16x16x32_bf16 v[88:91], v[170:173], v[186:189], 0
	v_mfma_f32_16x16x32_bf16 v[76:79], v[162:165], v[194:197], 0
	v_mfma_f32_16x16x32_bf16 v[72:75], v[170:173], v[194:197], 0
	v_mfma_f32_16x16x32_bf16 v[68:71], v[162:165], v[202:205], 0
	v_mfma_f32_16x16x32_bf16 v[64:67], v[170:173], v[202:205], 0
	v_mfma_f32_16x16x32_bf16 v[108:111], v[166:169], v[182:185], v[108:111]
	v_mfma_f32_16x16x32_bf16 v[104:107], v[174:177], v[182:185], v[104:107]
	v_mfma_f32_16x16x32_bf16 v[92:95], v[166:169], v[190:193], v[92:95]
	v_mfma_f32_16x16x32_bf16 v[88:91], v[174:177], v[190:193], v[88:91]
	v_mfma_f32_16x16x32_bf16 v[76:79], v[166:169], v[198:201], v[76:79]
	v_mfma_f32_16x16x32_bf16 v[72:75], v[174:177], v[198:201], v[72:75]
	v_mfma_f32_16x16x32_bf16 v[68:71], v[166:169], v[218:221], v[68:71]
	v_mfma_f32_16x16x32_bf16 v[64:67], v[174:177], v[218:221], v[64:67]
	s_setprio 0
	s_barrier
	s_add_i32 s43, s43, s22
	v_lshl_add_u64 v[158:159], s[16:17], 0, v[160:161]
	s_mov_b32 m0, s43
	ds_read_b128 v[178:181], v141 offset:16384
	ds_read_b128 v[182:185], v141 offset:17408
	ds_read_b128 v[186:189], v141 offset:18432
	ds_read_b128 v[190:193], v141 offset:19456
	ds_read_b128 v[194:197], v141 offset:20480
	ds_read_b128 v[198:201], v141 offset:21504
	ds_read_b128 v[202:205], v141 offset:22528
	ds_read_b128 v[218:221], v141 offset:23552
	global_load_lds_dwordx4 v[158:159], off
	s_add_i32 m0, s43, 0x2000
	s_add_u32 s46, s16, 0x100000
	v_lshl_add_u64 v[212:213], s[16:17], 0, v[128:129]
	s_addc_u32 s47, s17, 0
	s_add_i32 s43, s48, s22
	global_load_lds_dwordx4 v[212:213], off
	v_lshl_add_u64 v[222:223], s[46:47], 0, v[160:161]
	s_mov_b32 m0, s43
	v_lshl_add_u64 v[224:225], s[18:19], 0, v[130:131]
	global_load_lds_dwordx4 v[222:223], off
	v_lshl_add_u64 v[222:223], s[46:47], 0, v[128:129]
	s_add_i32 m0, s43, 0x2000
	s_nop 0
	global_load_lds_dwordx4 v[222:223], off
	v_lshl_add_u64 v[222:223], s[18:19], 0, v[132:133]
	s_mov_b32 m0, s23
	s_nop 0
	global_load_lds_dwordx4 v[222:223], off
	s_mov_b32 m0, s24
	s_nop 0
	global_load_lds_dwordx4 v[224:225], off
	s_waitcnt vmcnt(8)
	s_waitcnt lgkmcnt(0)
	s_barrier
	s_setprio 1
	s_waitcnt lgkmcnt(0)
	v_mfma_f32_16x16x32_bf16 v[60:63], v[142:145], v[178:181], 0
	v_mfma_f32_16x16x32_bf16 v[56:59], v[150:153], v[178:181], 0
	v_mfma_f32_16x16x32_bf16 v[52:55], v[142:145], v[186:189], 0
	v_mfma_f32_16x16x32_bf16 v[48:51], v[150:153], v[186:189], 0
	v_mfma_f32_16x16x32_bf16 v[36:39], v[142:145], v[194:197], 0
	v_mfma_f32_16x16x32_bf16 v[32:35], v[150:153], v[194:197], 0
	v_mfma_f32_16x16x32_bf16 v[20:23], v[142:145], v[202:205], 0
	v_mfma_f32_16x16x32_bf16 v[16:19], v[150:153], v[202:205], 0
	v_mfma_f32_16x16x32_bf16 v[60:63], v[146:149], v[182:185], v[60:63]
	v_mfma_f32_16x16x32_bf16 v[56:59], v[154:157], v[182:185], v[56:59]
	v_mfma_f32_16x16x32_bf16 v[52:55], v[146:149], v[190:193], v[52:55]
	v_mfma_f32_16x16x32_bf16 v[48:51], v[154:157], v[190:193], v[48:51]
	v_mfma_f32_16x16x32_bf16 v[36:39], v[146:149], v[198:201], v[36:39]
	v_mfma_f32_16x16x32_bf16 v[32:35], v[154:157], v[198:201], v[32:35]
	v_mfma_f32_16x16x32_bf16 v[20:23], v[146:149], v[218:221], v[20:23]
	v_mfma_f32_16x16x32_bf16 v[16:19], v[154:157], v[218:221], v[16:19]
	s_setprio 0
	s_setprio 1
	v_mfma_f32_16x16x32_bf16 v[44:47], v[162:165], v[178:181], 0
	v_mfma_f32_16x16x32_bf16 v[40:43], v[170:173], v[178:181], 0
	v_mfma_f32_16x16x32_bf16 v[28:31], v[162:165], v[186:189], 0
	v_mfma_f32_16x16x32_bf16 v[24:27], v[170:173], v[186:189], 0
	v_mfma_f32_16x16x32_bf16 v[12:15], v[162:165], v[194:197], 0
	v_mfma_f32_16x16x32_bf16 v[8:11], v[170:173], v[194:197], 0
	v_mfma_f32_16x16x32_bf16 v[4:7], v[162:165], v[202:205], 0
	v_mfma_f32_16x16x32_bf16 v[0:3], v[170:173], v[202:205], 0
	v_mfma_f32_16x16x32_bf16 v[44:47], v[166:169], v[182:185], v[44:47]
	v_mfma_f32_16x16x32_bf16 v[40:43], v[174:177], v[182:185], v[40:43]
	v_mfma_f32_16x16x32_bf16 v[28:31], v[166:169], v[190:193], v[28:31]
	v_mfma_f32_16x16x32_bf16 v[24:27], v[174:177], v[190:193], v[24:27]
	v_mfma_f32_16x16x32_bf16 v[12:15], v[166:169], v[198:201], v[12:15]
	v_mfma_f32_16x16x32_bf16 v[8:11], v[174:177], v[198:201], v[8:11]
	v_mfma_f32_16x16x32_bf16 v[4:7], v[166:169], v[218:221], v[4:7]
	v_mfma_f32_16x16x32_bf16 v[0:3], v[174:177], v[218:221], v[0:3]
	s_setprio 0
	s_barrier
	s_add_i32 s43, 0, 0x18000
	s_add_i32 s46, 0, 0x1c000
	v_add_u32_e32 v154, s43, v139
	v_add_u32_e32 v174, s46, v139
	ds_read_b128 v[142:145], v154
	ds_read_b128 v[146:149], v154 offset:1024
	ds_read_b128 v[150:153], v154 offset:2048
	ds_read_b128 v[154:157], v154 offset:3072
	ds_read_b128 v[162:165], v174
	ds_read_b128 v[166:169], v174 offset:1024
	ds_read_b128 v[170:173], v174 offset:2048
	ds_read_b128 v[174:177], v174 offset:3072
	s_add_u32 s18, s18, 0x100000
	s_addc_u32 s19, s19, 0
	s_mov_b32 m0, s25
	v_lshl_add_u64 v[226:227], s[18:19], 0, v[132:133]
	ds_read_b128 v[178:181], v141 offset:32768
	ds_read_b128 v[182:185], v141 offset:33792
	ds_read_b128 v[186:189], v141 offset:34816
	ds_read_b128 v[190:193], v141 offset:35840
	ds_read_b128 v[194:197], v141 offset:36864
	ds_read_b128 v[198:201], v141 offset:37888
	ds_read_b128 v[202:205], v141 offset:38912
	ds_read_b128 v[218:221], v141 offset:39936
	global_load_lds_dwordx4 v[226:227], off
	v_lshl_add_u64 v[226:227], s[18:19], 0, v[130:131]
	s_mov_b32 m0, s26
	s_nop 0
	global_load_lds_dwordx4 v[226:227], off
	s_waitcnt vmcnt(8)
	s_waitcnt lgkmcnt(0)
	s_barrier
	s_setprio 1
	s_waitcnt lgkmcnt(0)
	v_mfma_f32_16x16x32_bf16 v[124:127], v[142:145], v[178:181], v[124:127]
	v_mfma_f32_16x16x32_bf16 v[120:123], v[150:153], v[178:181], v[120:123]
	v_mfma_f32_16x16x32_bf16 v[116:119], v[142:145], v[186:189], v[116:119]
	v_mfma_f32_16x16x32_bf16 v[112:115], v[150:153], v[186:189], v[112:115]
	v_mfma_f32_16x16x32_bf16 v[100:103], v[142:145], v[194:197], v[100:103]
	v_mfma_f32_16x16x32_bf16 v[96:99], v[150:153], v[194:197], v[96:99]
	v_mfma_f32_16x16x32_bf16 v[84:87], v[142:145], v[202:205], v[84:87]
	v_mfma_f32_16x16x32_bf16 v[80:83], v[150:153], v[202:205], v[80:83]
	v_mfma_f32_16x16x32_bf16 v[124:127], v[146:149], v[182:185], v[124:127]
	v_mfma_f32_16x16x32_bf16 v[120:123], v[154:157], v[182:185], v[120:123]
	v_mfma_f32_16x16x32_bf16 v[116:119], v[146:149], v[190:193], v[116:119]
	v_mfma_f32_16x16x32_bf16 v[112:115], v[154:157], v[190:193], v[112:115]
	v_mfma_f32_16x16x32_bf16 v[100:103], v[146:149], v[198:201], v[100:103]
	v_mfma_f32_16x16x32_bf16 v[96:99], v[154:157], v[198:201], v[96:99]
	v_mfma_f32_16x16x32_bf16 v[84:87], v[146:149], v[218:221], v[84:87]
	v_mfma_f32_16x16x32_bf16 v[80:83], v[154:157], v[218:221], v[80:83]
	s_setprio 0
	s_setprio 1
	v_mfma_f32_16x16x32_bf16 v[108:111], v[162:165], v[178:181], v[108:111]
	v_mfma_f32_16x16x32_bf16 v[104:107], v[170:173], v[178:181], v[104:107]
	v_mfma_f32_16x16x32_bf16 v[92:95], v[162:165], v[186:189], v[92:95]
	v_mfma_f32_16x16x32_bf16 v[88:91], v[170:173], v[186:189], v[88:91]
	v_mfma_f32_16x16x32_bf16 v[76:79], v[162:165], v[194:197], v[76:79]
	v_mfma_f32_16x16x32_bf16 v[72:75], v[170:173], v[194:197], v[72:75]
	v_mfma_f32_16x16x32_bf16 v[68:71], v[162:165], v[202:205], v[68:71]
	v_mfma_f32_16x16x32_bf16 v[64:67], v[170:173], v[202:205], v[64:67]
	v_mfma_f32_16x16x32_bf16 v[108:111], v[166:169], v[182:185], v[108:111]
	v_mfma_f32_16x16x32_bf16 v[104:107], v[174:177], v[182:185], v[104:107]
	v_mfma_f32_16x16x32_bf16 v[92:95], v[166:169], v[190:193], v[92:95]
	v_mfma_f32_16x16x32_bf16 v[88:91], v[174:177], v[190:193], v[88:91]
	v_mfma_f32_16x16x32_bf16 v[76:79], v[166:169], v[198:201], v[76:79]
	v_mfma_f32_16x16x32_bf16 v[72:75], v[174:177], v[198:201], v[72:75]
	v_mfma_f32_16x16x32_bf16 v[68:71], v[166:169], v[218:221], v[68:71]
	v_mfma_f32_16x16x32_bf16 v[64:67], v[174:177], v[218:221], v[64:67]
	s_setprio 0
	s_barrier
	s_add_i32 s18, s43, s22
	v_lshl_add_u64 v[158:159], v[158:159], 0, vcc
	s_mov_b32 m0, s18
	ds_read_b128 v[178:181], v141 offset:49152
	ds_read_b128 v[182:185], v141 offset:50176
	ds_read_b128 v[186:189], v141 offset:51200
	ds_read_b128 v[190:193], v141 offset:52224
	ds_read_b128 v[194:197], v141 offset:53248
	ds_read_b128 v[198:201], v141 offset:54272
	ds_read_b128 v[202:205], v141 offset:55296
	ds_read_b128 v[218:221], v141 offset:56320
	global_load_lds_dwordx4 v[158:159], off
	s_add_i32 m0, s18, 0x2000
	s_add_u32 s16, s16, 0x100080
	v_lshl_add_u64 v[158:159], v[212:213], 0, vcc
	s_addc_u32 s17, s17, 0
	s_add_i32 s18, s46, s22
	global_load_lds_dwordx4 v[158:159], off
	v_lshl_add_u64 v[158:159], s[16:17], 0, v[160:161]
	s_mov_b32 m0, s18
	s_nop 0
	global_load_lds_dwordx4 v[158:159], off
	v_lshl_add_u64 v[158:159], s[16:17], 0, v[128:129]
	s_add_i32 m0, s18, 0x2000
	s_nop 0
	global_load_lds_dwordx4 v[158:159], off
	v_lshl_add_u64 v[158:159], v[222:223], 0, vcc
	s_mov_b32 m0, s28
	s_nop 0
	global_load_lds_dwordx4 v[158:159], off
	v_lshl_add_u64 v[158:159], v[224:225], 0, vcc
	s_mov_b32 m0, s29
	s_nop 0
	global_load_lds_dwordx4 v[158:159], off
	s_waitcnt vmcnt(8)
	s_waitcnt lgkmcnt(0)
	s_barrier
	s_setprio 1
	s_waitcnt lgkmcnt(0)
	v_mfma_f32_16x16x32_bf16 v[60:63], v[142:145], v[178:181], v[60:63]
	v_mfma_f32_16x16x32_bf16 v[56:59], v[150:153], v[178:181], v[56:59]
	v_mfma_f32_16x16x32_bf16 v[52:55], v[142:145], v[186:189], v[52:55]
	v_mfma_f32_16x16x32_bf16 v[48:51], v[150:153], v[186:189], v[48:51]
	v_mfma_f32_16x16x32_bf16 v[36:39], v[142:145], v[194:197], v[36:39]
	v_mfma_f32_16x16x32_bf16 v[32:35], v[150:153], v[194:197], v[32:35]
	v_mfma_f32_16x16x32_bf16 v[20:23], v[142:145], v[202:205], v[20:23]
	v_mfma_f32_16x16x32_bf16 v[16:19], v[150:153], v[202:205], v[16:19]
	v_mfma_f32_16x16x32_bf16 v[60:63], v[146:149], v[182:185], v[60:63]
	v_mfma_f32_16x16x32_bf16 v[56:59], v[154:157], v[182:185], v[56:59]
	v_mfma_f32_16x16x32_bf16 v[52:55], v[146:149], v[190:193], v[52:55]
	v_mfma_f32_16x16x32_bf16 v[48:51], v[154:157], v[190:193], v[48:51]
	v_mfma_f32_16x16x32_bf16 v[36:39], v[146:149], v[198:201], v[36:39]
	v_mfma_f32_16x16x32_bf16 v[32:35], v[154:157], v[198:201], v[32:35]
	v_mfma_f32_16x16x32_bf16 v[20:23], v[146:149], v[218:221], v[20:23]
	v_mfma_f32_16x16x32_bf16 v[16:19], v[154:157], v[218:221], v[16:19]
	s_setprio 0
	s_setprio 1
	v_mfma_f32_16x16x32_bf16 v[44:47], v[162:165], v[178:181], v[44:47]
	v_mfma_f32_16x16x32_bf16 v[40:43], v[170:173], v[178:181], v[40:43]
	v_mfma_f32_16x16x32_bf16 v[28:31], v[162:165], v[186:189], v[28:31]
	v_mfma_f32_16x16x32_bf16 v[24:27], v[170:173], v[186:189], v[24:27]
	v_mfma_f32_16x16x32_bf16 v[12:15], v[162:165], v[194:197], v[12:15]
	v_mfma_f32_16x16x32_bf16 v[8:11], v[170:173], v[194:197], v[8:11]
	v_mfma_f32_16x16x32_bf16 v[4:7], v[162:165], v[202:205], v[4:7]
	v_mfma_f32_16x16x32_bf16 v[0:3], v[170:173], v[202:205], v[0:3]
	v_mfma_f32_16x16x32_bf16 v[44:47], v[166:169], v[182:185], v[44:47]
	v_mfma_f32_16x16x32_bf16 v[40:43], v[174:177], v[182:185], v[40:43]
	v_mfma_f32_16x16x32_bf16 v[28:31], v[166:169], v[190:193], v[28:31]
	v_mfma_f32_16x16x32_bf16 v[24:27], v[174:177], v[190:193], v[24:27]
	v_mfma_f32_16x16x32_bf16 v[12:15], v[166:169], v[198:201], v[12:15]
	v_mfma_f32_16x16x32_bf16 v[8:11], v[174:177], v[198:201], v[8:11]
	v_mfma_f32_16x16x32_bf16 v[4:7], v[166:169], v[218:221], v[4:7]
	v_mfma_f32_16x16x32_bf16 v[0:3], v[174:177], v[218:221], v[0:3]
	s_setprio 0
	s_barrier
	s_add_i32 s42, s42, 2
	s_add_u32 s14, s14, 0x100
	s_addc_u32 s15, s15, 0
	s_add_u32 s40, s40, 0x100
	s_addc_u32 s41, s41, 0
	s_cmp_gt_u32 s42, 61
